# k43 + POST rope partner exchanges (lane^2, lane^4) via DPP movs instead of ds_bpermute
# baseline (speedup 1.0000x reference)
; #define LAS __attribute__((address_space(3)))
; DI float sum32(float v) { v += __shfl_xor(v, 16); return sum16(v); }
; DI f32x2 unpk(unsigned w) { f32x2 r = {bflo(w), bfhi(w)}; return r; }
; template <int HP> DI void rope2(f32x2& x, int hl, const LAS f32x2* cs) {
;   const float pa = __shfl_xor(x[0], HP), pb = __shfl_xor(x[1], HP);
;   if (hl < HP) { const f32x2 c0 = cs[2 * hl], c1 = cs[2 * hl + 1]; x[0] = x[0] * c0[0] - pa * c0[1]; x[1] = x[1] * c1[0] - pb * c1[1]; }
; DI void post_unit(const Params& p, int l, int unit, LAS unsigned char* lds) {
;     ...
;     for (int hf = 0; hf < 2; ++hf) { const u16* rowl = proj + (tok0 + w * 8 + 2 * tp + hf) * NP;
; #pragma unroll
;       for (int s = 0; s < 16; ++s) raw2[hf][s] = *(const unsigned*)(rowl + segcol[s] + 2 * lane); }
; #pragma unroll
;     for (int hf = 0; hf < 2; ++hf) {
;     const int t = w * 8 + 2 * tp + hf; u16* row = proj + (tok0 + t) * NP;
; #pragma unroll
;     for (int s = 0; s < 16; ++s) {
;       f32x2 x = unpk(raw2[hf][s]); u16* pp = row + segcol[s] + 2 * lane;
;       if (s < 2) {
;         const float rs = rsqrtf(sum32(x[0] * x[0] + x[1] * x[1]) * (1.0f / 64.0f) + EPS);
;         x[0] *= rs * qna[2 * hl]; x[1] *= rs * qna[2 * hl + 1]; rope2<4>(x, hl, cs16 + t * 8);
.LBB0_150:
	v_lshl_add_u64 v[18:19], v[12:13], 0, v[0:1]
	v_add_co_u32_e32 v20, vcc, 0xa000000, v18
	s_mov_b32 s2, 0xa001000
	s_waitcnt lgkmcnt(0)
	v_addc_co_u32_e32 v21, vcc, 0, v19, vcc
	global_load_dword v49, v[20:21], off
	v_add_co_u32_e32 v22, vcc, s2, v18
	s_mov_b32 s2, 0xa003000
	s_nop 0
	v_addc_co_u32_e32 v23, vcc, 0, v19, vcc
	v_add_co_u32_e32 v42, vcc, s77, v18
	global_load_dword v59, v[20:21], off offset:512
	global_load_dword v70, v[20:21], off offset:768
	global_load_dword v69, v[20:21], off offset:1024
	global_load_dword v68, v[20:21], off offset:1280
	global_load_dword v67, v[20:21], off offset:1536
	global_load_dword v58, v[20:21], off offset:1792
	global_load_dword v71, v[20:21], off offset:256
	v_addc_co_u32_e32 v43, vcc, 0, v19, vcc
	global_load_dword v56, v[20:21], off offset:2432
	global_load_dword v66, v[20:21], off offset:2688
	global_load_dword v65, v[20:21], off offset:2944
	global_load_dword v64, v[20:21], off offset:3200
	global_load_dword v54, v[22:23], off offset:384
	global_load_dword v63, v[22:23], off offset:640
	global_load_dword v62, v[22:23], off offset:896
	global_load_dword v61, v[22:23], off offset:1152
	v_add_co_u32_e32 v20, vcc, s2, v18
	global_load_dword v60, v[42:43], off offset:512
	global_load_dword v57, v[42:43], off offset:768
	global_load_dword v55, v[42:43], off offset:1024
	global_load_dword v53, v[42:43], off offset:1280
	global_load_dword v52, v[42:43], off offset:1536
	global_load_dword v51, v[42:43], off offset:1792
	global_load_dword v50, v[42:43], off offset:2048
	global_load_dword v48, v[42:43], off offset:2304
	v_addc_co_u32_e32 v21, vcc, 0, v19, vcc
	global_load_dword v47, v[42:43], off offset:2944
	global_load_dword v46, v[42:43], off offset:3200
	global_load_dword v45, v[42:43], off offset:3456
	global_load_dword v44, v[42:43], off offset:3712
	s_nop 0
	global_load_dword v43, v[20:21], off offset:896
	global_load_dword v42, v[20:21], off offset:1152
	global_load_dword v41, v[20:21], off offset:1408
	global_load_dword v3, v[20:21], off offset:1664
	s_waitcnt vmcnt(31)
	v_and_b32_e32 v21, 0xffff0000, v49
	v_lshlrev_b32_e32 v20, 16, v49
	v_pk_mul_f32 v[22:23], v[20:21], v[20:21]
	s_nop 0
	v_add_f32_e32 v22, v22, v23
	v_mov_b32_e32 v23, v22
	s_nop 1
	v_permlane16_swap_b32_e32 v22, v23
	v_add_f32_e32 v22, v22, v23
	s_nop 1
	v_add_f32_dpp v22, v22, v22 row_ror:8 row_mask:0xf bank_mask:0xf
	s_nop 1
	v_add_f32_dpp v22, v22, v22 row_ror:4 row_mask:0xf bank_mask:0xf
	s_nop 1
	v_add_f32_dpp v22, v22, v22 quad_perm:[2,3,0,1] row_mask:0xf bank_mask:0xf
	s_nop 1
	v_add_f32_dpp v22, v22, v22 quad_perm:[1,0,3,2] row_mask:0xf bank_mask:0xf
	v_fmamk_f32 v22, v22, 0x3c800000, v170
	v_mul_f32_e32 v23, 0x4b800000, v22
	v_cmp_gt_f32_e32 vcc, s33, v22
	s_nop 1
	v_cndmask_b32_e32 v22, v22, v23, vcc
	v_rsq_f32_e32 v22, v22
	s_nop 0
	v_mul_f32_e32 v23, 0x45800000, v22
	v_cndmask_b32_e32 v22, v22, v23, vcc
	v_pk_mul_f32 v[22:23], v[4:5], v[22:23] op_sel_hi:[1,0]
	s_nop 0
	v_pk_mul_f32 v[22:23], v[22:23], v[20:21]
	s_nop 1
	v_mov_b32_dpp v20, v22 row_half_mirror row_mask:0xf bank_mask:0xf
	v_mov_b32_dpp v21, v23 row_half_mirror row_mask:0xf bank_mask:0xf
	s_nop 0
	v_mov_b32_dpp v20, v20 quad_perm:[3,2,1,0] row_mask:0xf bank_mask:0xf
	v_mov_b32_dpp v21, v21 quad_perm:[3,2,1,0] row_mask:0xf bank_mask:0xf
	s_and_saveexec_b64 s[2:3], s[12:13]
	s_xor_b64 s[18:19], exec, s[2:3]
	s_cbranch_execz .LBB0_154
	s_and_saveexec_b64 s[30:31], s[14:15]
	s_cbranch_execz .LBB0_153
	v_add_u32_e32 v49, 0, v35
	ds_read_b128 v[72:75], v49
	s_waitcnt lgkmcnt(0)
	v_pk_mul_f32 v[76:77], v[22:23], v[72:73]
	v_mul_f32_e32 v22, v73, v20
	v_mov_b32_e32 v20, v23
	v_pk_mul_f32 v[20:21], v[20:21], v[74:75]
	s_nop 0
	v_mov_b32_e32 v77, v20
	v_mov_b32_e32 v23, v21
	v_pk_add_f32 v[22:23], v[76:77], v[22:23]

; #define LAS __attribute__((address_space(3)))
; DI unsigned pk2(float lo, float hi) { f32x2 x = {lo, hi}; return __builtin_bit_cast(unsigned, __builtin_convertvector(x, bf16x2_t)); }
; DI float sum32(float v) { v += __shfl_xor(v, 16); return sum16(v); }
; DI f32x2 unpk(unsigned w) { f32x2 r = {bflo(w), bfhi(w)}; return r; }
; template <int HP> DI void rope2(f32x2& x, int hl, const LAS f32x2* cs) {
;   const float pa = __shfl_xor(x[0], HP), pb = __shfl_xor(x[1], HP);
;   if (hl < HP) { const f32x2 c0 = cs[2 * hl], c1 = cs[2 * hl + 1]; x[0] = x[0] * c0[0] - pa * c0[1]; x[1] = x[1] * c1[0] - pb * c1[1]; }
; DI void post_unit(const Params& p, int l, int unit, LAS unsigned char* lds) {
;     ...
;       f32x2 x = unpk(raw2[hf][s]); u16* pp = row + segcol[s] + 2 * lane;
;       if (s < 2) {
;         const float rs = rsqrtf(sum32(x[0] * x[0] + x[1] * x[1]) * (1.0f / 64.0f) + EPS);
;         x[0] *= rs * qna[2 * hl]; x[1] *= rs * qna[2 * hl + 1]; rope2<4>(x, hl, cs16 + t * 8);
;         x *= LOG2E * 0.125f; *(unsigned*)pp = pk2(x[0], x[1]);
.LBB0_156:
	s_or_b64 exec, exec, s[18:19]
	s_mov_b64 s[2:3], 0xa000000
	s_waitcnt lgkmcnt(0)
	v_lshl_add_u64 v[20:21], v[18:19], 0, s[2:3]
	s_mov_b32 s2, 0x3e38aa3b
	v_pk_mul_f32 v[22:23], v[22:23], s[2:3] op_sel_hi:[1,0]
	s_nop 0
	v_cvt_pk_bf16_f32 v22, v22, v23
	global_store_dword v[20:21], v22, off
	s_waitcnt vmcnt(25)
	v_and_b32_e32 v21, 0xffff0000, v71
	v_lshlrev_b32_e32 v20, 16, v71
	v_pk_mul_f32 v[22:23], v[20:21], v[20:21]
	s_nop 0
	v_add_f32_e32 v22, v22, v23
	v_mov_b32_e32 v23, v22
	s_nop 1
	v_permlane16_swap_b32_e32 v22, v23
	v_add_f32_e32 v22, v22, v23
	s_nop 1
	v_add_f32_dpp v22, v22, v22 row_ror:8 row_mask:0xf bank_mask:0xf
	s_nop 1
	v_add_f32_dpp v22, v22, v22 row_ror:4 row_mask:0xf bank_mask:0xf
	s_nop 1
	v_add_f32_dpp v22, v22, v22 quad_perm:[2,3,0,1] row_mask:0xf bank_mask:0xf
	s_nop 1
	v_add_f32_dpp v22, v22, v22 quad_perm:[1,0,3,2] row_mask:0xf bank_mask:0xf
	v_fmamk_f32 v22, v22, 0x3c800000, v170
	v_cmp_gt_f32_e32 vcc, s33, v22
	v_mul_f32_e32 v23, 0x4b800000, v22
	s_nop 0
	v_cndmask_b32_e32 v22, v22, v23, vcc
	v_rsq_f32_e32 v22, v22
	s_nop 0
	v_mul_f32_e32 v23, 0x45800000, v22
	v_cndmask_b32_e32 v22, v22, v23, vcc
	v_pk_mul_f32 v[22:23], v[4:5], v[22:23] op_sel_hi:[1,0]
	s_nop 0
	v_pk_mul_f32 v[22:23], v[22:23], v[20:21]
	s_nop 1
	v_mov_b32_dpp v20, v22 row_half_mirror row_mask:0xf bank_mask:0xf
	v_mov_b32_dpp v21, v23 row_half_mirror row_mask:0xf bank_mask:0xf
	s_nop 0
	v_mov_b32_dpp v20, v20 quad_perm:[3,2,1,0] row_mask:0xf bank_mask:0xf
	v_mov_b32_dpp v21, v21 quad_perm:[3,2,1,0] row_mask:0xf bank_mask:0xf
	s_and_saveexec_b64 s[2:3], s[12:13]
	s_xor_b64 s[18:19], exec, s[2:3]
	s_cbranch_execz .LBB0_160
	s_and_saveexec_b64 s[30:31], s[14:15]
	s_cbranch_execz .LBB0_159
	ds_read_b128 v[72:75], v49
	s_waitcnt lgkmcnt(0)
	v_pk_mul_f32 v[76:77], v[22:23], v[72:73]
	v_mul_f32_e32 v22, v73, v20
	v_mov_b32_e32 v20, v23
	v_pk_mul_f32 v[20:21], v[20:21], v[74:75]
	s_nop 0
	v_mov_b32_e32 v77, v20
	v_mov_b32_e32 v23, v21
	v_pk_add_f32 v[22:23], v[76:77], v[22:23]

; #define LAS __attribute__((address_space(3)))
; DI unsigned pk2(float lo, float hi) { f32x2 x = {lo, hi}; return __builtin_bit_cast(unsigned, __builtin_convertvector(x, bf16x2_t)); }
; DI float sum64(float v) { v += __shfl_xor(v, 32); return sum32(v); }
; DI void post_unit(const Params& p, int l, int unit, LAS unsigned char* lds) {
;     ...
;       } else if (s == 2) {
;         const float rs = rsqrtf(sum64(x[0] * x[0] + x[1] * x[1]) * (1.0f / 128.0f) + EPS);
;         *(LAS unsigned*)(At + t * 272 + lane * 4) = pk2(x[0] * rs, x[1] * rs);
;       } else if (s < 7) {
;         rope2<4>(x, hl, cs16 + t * 8); *(unsigned*)pp = pk2(x[0], x[1]);
.LBB0_162:
	s_or_b64 exec, exec, s[18:19]
	s_mov_b64 s[2:3], 0xa000100
	s_waitcnt lgkmcnt(0)
	v_lshl_add_u64 v[20:21], v[18:19], 0, s[2:3]
	s_mov_b32 s2, 0x3e38aa3b
	v_pk_mul_f32 v[22:23], v[22:23], s[2:3] op_sel_hi:[1,0]
	s_nop 0
	v_cvt_pk_bf16_f32 v22, v22, v23
	global_store_dword v[20:21], v22, off
	v_lshlrev_b32_e32 v20, 16, v59
	v_and_b32_e32 v21, 0xffff0000, v59
	v_pk_mul_f32 v[22:23], v[20:21], v[20:21]
	v_add_u32_e32 v59, 0, v33
	v_add_f32_e32 v22, v22, v23
	v_mov_b32_e32 v23, v22
	s_nop 1
	v_permlane32_swap_b32_e32 v22, v23
	v_add_f32_e32 v22, v22, v23
	v_mov_b32_e32 v23, v22
	s_nop 1
	v_permlane16_swap_b32_e32 v22, v23
	v_add_f32_e32 v22, v22, v23
	s_nop 1
	v_add_f32_dpp v22, v22, v22 row_ror:8 row_mask:0xf bank_mask:0xf
	s_nop 1
	v_add_f32_dpp v22, v22, v22 row_ror:4 row_mask:0xf bank_mask:0xf
	s_nop 1
	v_add_f32_dpp v22, v22, v22 quad_perm:[2,3,0,1] row_mask:0xf bank_mask:0xf
	s_nop 1
	v_add_f32_dpp v22, v22, v22 quad_perm:[1,0,3,2] row_mask:0xf bank_mask:0xf
	v_fmamk_f32 v22, v22, 0x3c000000, v170
	v_cmp_gt_f32_e32 vcc, s33, v22
	v_mul_f32_e32 v23, 0x4b800000, v22
	s_nop 0
	v_cndmask_b32_e32 v22, v22, v23, vcc
	v_rsq_f32_e32 v22, v22
	s_nop 0
	v_mul_f32_e32 v23, 0x45800000, v22
	v_cndmask_b32_e32 v22, v22, v23, vcc
	v_pk_mul_f32 v[20:21], v[22:23], v[20:21] op_sel_hi:[0,1]
	v_cvt_pk_bf16_f32 v20, v20, v21
	ds_write_b32 v59, v20
	v_lshlrev_b32_e32 v20, 16, v70
	v_and_b32_e32 v21, 0xffff0000, v70
	s_nop 1
	v_mov_b32_dpp v70, v20 row_half_mirror row_mask:0xf bank_mask:0xf
	v_mov_b32_dpp v23, v21 row_half_mirror row_mask:0xf bank_mask:0xf
	s_nop 0
	v_mov_b32_dpp v70, v70 quad_perm:[3,2,1,0] row_mask:0xf bank_mask:0xf
	v_mov_b32_dpp v23, v23 quad_perm:[3,2,1,0] row_mask:0xf bank_mask:0xf
	s_and_saveexec_b64 s[2:3], s[12:13]
	s_xor_b64 s[18:19], exec, s[2:3]
	s_cbranch_execz .LBB0_166
	s_and_saveexec_b64 s[30:31], s[14:15]
	s_cbranch_execz .LBB0_165
	ds_read_b128 v[72:75], v49
	v_mov_b32_e32 v22, v21
	s_waitcnt lgkmcnt(0)
	v_pk_mul_f32 v[22:23], v[74:75], v[22:23]
	v_mul_f32_e32 v20, v72, v20
	v_mul_f32_e32 v70, v73, v70
	v_mov_b32_e32 v21, v22
	v_mov_b32_e32 v71, v23
	v_pk_add_f32 v[20:21], v[20:21], v[70:71]

; DI unsigned pk2(float lo, float hi) { f32x2 x = {lo, hi}; return __builtin_bit_cast(unsigned, __builtin_convertvector(x, bf16x2_t)); }
; DI void post_unit(const Params& p, int l, int unit, LAS unsigned char* lds) {
;     ...
;       } else if (s < 7) {
;         rope2<4>(x, hl, cs16 + t * 8); *(unsigned*)pp = pk2(x[0], x[1]);
.LBB0_168:
	s_or_b64 exec, exec, s[18:19]
	s_mov_b64 s[2:3], 0xa000300
	s_waitcnt lgkmcnt(0)
	v_lshl_add_u64 v[22:23], v[18:19], 0, s[2:3]
	v_cvt_pk_bf16_f32 v20, v20, v21
	global_store_dword v[22:23], v20, off
	v_lshlrev_b32_e32 v20, 16, v69
	v_and_b32_e32 v21, 0xffff0000, v69
	s_nop 1
	v_mov_b32_dpp v69, v20 row_half_mirror row_mask:0xf bank_mask:0xf
	v_mov_b32_dpp v23, v21 row_half_mirror row_mask:0xf bank_mask:0xf
	s_nop 0
	v_mov_b32_dpp v69, v69 quad_perm:[3,2,1,0] row_mask:0xf bank_mask:0xf
	v_mov_b32_dpp v23, v23 quad_perm:[3,2,1,0] row_mask:0xf bank_mask:0xf
	s_and_saveexec_b64 s[2:3], s[12:13]
	s_xor_b64 s[18:19], exec, s[2:3]
	s_cbranch_execz .LBB0_172
	s_and_saveexec_b64 s[30:31], s[14:15]
	s_cbranch_execz .LBB0_171
	ds_read_b128 v[70:73], v49
	v_mov_b32_e32 v22, v21
	s_waitcnt lgkmcnt(0)
	v_pk_mul_f32 v[22:23], v[72:73], v[22:23]
	v_mul_f32_e32 v20, v70, v20
	v_mul_f32_e32 v70, v71, v69
	v_mov_b32_e32 v21, v22
	v_mov_b32_e32 v71, v23
	v_pk_add_f32 v[20:21], v[20:21], v[70:71]

; DI unsigned pk2(float lo, float hi) { f32x2 x = {lo, hi}; return __builtin_bit_cast(unsigned, __builtin_convertvector(x, bf16x2_t)); }
; DI void post_unit(const Params& p, int l, int unit, LAS unsigned char* lds) {
;     ...
;       } else if (s < 7) {
;         rope2<4>(x, hl, cs16 + t * 8); *(unsigned*)pp = pk2(x[0], x[1]);
.LBB0_174:
	s_or_b64 exec, exec, s[18:19]
	s_mov_b64 s[2:3], 0xa000400
	s_waitcnt lgkmcnt(0)
	v_lshl_add_u64 v[22:23], v[18:19], 0, s[2:3]
	v_cvt_pk_bf16_f32 v20, v20, v21
	global_store_dword v[22:23], v20, off
	v_lshlrev_b32_e32 v20, 16, v68
	v_and_b32_e32 v21, 0xffff0000, v68
	s_nop 1
	v_mov_b32_dpp v68, v20 row_half_mirror row_mask:0xf bank_mask:0xf
	v_mov_b32_dpp v23, v21 row_half_mirror row_mask:0xf bank_mask:0xf
	s_nop 0
	v_mov_b32_dpp v68, v68 quad_perm:[3,2,1,0] row_mask:0xf bank_mask:0xf
	v_mov_b32_dpp v23, v23 quad_perm:[3,2,1,0] row_mask:0xf bank_mask:0xf
	s_and_saveexec_b64 s[2:3], s[12:13]
	s_xor_b64 s[18:19], exec, s[2:3]
	s_cbranch_execz .LBB0_178
	s_and_saveexec_b64 s[30:31], s[14:15]
	s_cbranch_execz .LBB0_177
	ds_read_b128 v[70:73], v49
	v_mov_b32_e32 v22, v21
	s_waitcnt lgkmcnt(0)
	v_pk_mul_f32 v[22:23], v[72:73], v[22:23]
	v_mul_f32_e32 v20, v70, v20
	v_mul_f32_e32 v68, v71, v68
	v_mov_b32_e32 v21, v22
	v_mov_b32_e32 v69, v23
	v_pk_add_f32 v[20:21], v[20:21], v[68:69]

; DI unsigned pk2(float lo, float hi) { f32x2 x = {lo, hi}; return __builtin_bit_cast(unsigned, __builtin_convertvector(x, bf16x2_t)); }
; DI void post_unit(const Params& p, int l, int unit, LAS unsigned char* lds) {
;     ...
;       } else if (s < 7) {
;         rope2<4>(x, hl, cs16 + t * 8); *(unsigned*)pp = pk2(x[0], x[1]);
.LBB0_180:
	s_or_b64 exec, exec, s[18:19]
	s_mov_b64 s[2:3], 0xa000500
	s_waitcnt lgkmcnt(0)
	v_lshl_add_u64 v[22:23], v[18:19], 0, s[2:3]
	v_cvt_pk_bf16_f32 v20, v20, v21
	global_store_dword v[22:23], v20, off
	v_lshlrev_b32_e32 v20, 16, v67
	v_and_b32_e32 v21, 0xffff0000, v67
	s_nop 1
	v_mov_b32_dpp v67, v20 row_half_mirror row_mask:0xf bank_mask:0xf
	v_mov_b32_dpp v23, v21 row_half_mirror row_mask:0xf bank_mask:0xf
	s_nop 0
	v_mov_b32_dpp v67, v67 quad_perm:[3,2,1,0] row_mask:0xf bank_mask:0xf
	v_mov_b32_dpp v23, v23 quad_perm:[3,2,1,0] row_mask:0xf bank_mask:0xf
	s_and_saveexec_b64 s[2:3], s[12:13]
	s_xor_b64 s[18:19], exec, s[2:3]
	s_cbranch_execz .LBB0_184
	s_and_saveexec_b64 s[30:31], s[14:15]
	s_cbranch_execz .LBB0_183
	ds_read_b128 v[68:71], v49
	v_mov_b32_e32 v22, v21
	s_waitcnt lgkmcnt(0)
	v_pk_mul_f32 v[22:23], v[70:71], v[22:23]
	v_mul_f32_e32 v20, v68, v20
	v_mul_f32_e32 v68, v69, v67
	v_mov_b32_e32 v21, v22
	v_mov_b32_e32 v69, v23
	v_pk_add_f32 v[20:21], v[20:21], v[68:69]

; DI unsigned pk2(float lo, float hi) { f32x2 x = {lo, hi}; return __builtin_bit_cast(unsigned, __builtin_convertvector(x, bf16x2_t)); }
; DI float sum32(float v) { v += __shfl_xor(v, 16); return sum16(v); }
; DI void post_unit(const Params& p, int l, int unit, LAS unsigned char* lds) {
;     ...
;         rope2<4>(x, hl, cs16 + t * 8); *(unsigned*)pp = pk2(x[0], x[1]);
;       } else if (s == 7) {
;         const float rs = rsqrtf(sum32(x[0] * x[0] + x[1] * x[1]) * (1.0f / 64.0f) + EPS);
;         x *= rs; rope2<4>(x, hl, cs16 + t * 8); if (lane < 32) *(unsigned*)((u16*)(p.ws + WS_KIC) + (tok0 + t) * 64 + 2 * lane) = pk2(x[0], x[1]);
.LBB0_186:
	s_or_b64 exec, exec, s[18:19]
	s_mov_b64 s[2:3], 0xa000600
	s_waitcnt lgkmcnt(0)
	v_lshl_add_u64 v[22:23], v[18:19], 0, s[2:3]
	v_cvt_pk_bf16_f32 v20, v20, v21
	global_store_dword v[22:23], v20, off
	v_lshlrev_b32_e32 v20, 16, v58
	v_and_b32_e32 v21, 0xffff0000, v58
	v_pk_mul_f32 v[22:23], v[20:21], v[20:21]
	s_nop 0
	v_add_f32_e32 v22, v22, v23
	v_mov_b32_e32 v23, v22
	s_nop 1
	v_permlane16_swap_b32_e32 v22, v23
	v_add_f32_e32 v22, v22, v23
	s_nop 1
	v_add_f32_dpp v22, v22, v22 row_ror:8 row_mask:0xf bank_mask:0xf
	s_nop 1
	v_add_f32_dpp v22, v22, v22 row_ror:4 row_mask:0xf bank_mask:0xf
	s_nop 1
	v_add_f32_dpp v22, v22, v22 quad_perm:[2,3,0,1] row_mask:0xf bank_mask:0xf
	s_nop 1
	v_add_f32_dpp v22, v22, v22 quad_perm:[1,0,3,2] row_mask:0xf bank_mask:0xf
	v_fmamk_f32 v22, v22, 0x3c800000, v170
	v_cmp_gt_f32_e32 vcc, s33, v22
	v_mul_f32_e32 v23, 0x4b800000, v22
	s_nop 0
	v_cndmask_b32_e32 v22, v22, v23, vcc
	v_rsq_f32_e32 v22, v22
	s_nop 0
	v_mul_f32_e32 v23, 0x45800000, v22
	v_cndmask_b32_e32 v22, v22, v23, vcc
	v_pk_mul_f32 v[20:21], v[22:23], v[20:21] op_sel_hi:[0,1]
	s_nop 1
	v_mov_b32_dpp v22, v20 row_half_mirror row_mask:0xf bank_mask:0xf
	v_mov_b32_dpp v23, v21 row_half_mirror row_mask:0xf bank_mask:0xf
	s_nop 0
	v_mov_b32_dpp v22, v22 quad_perm:[3,2,1,0] row_mask:0xf bank_mask:0xf
	v_mov_b32_dpp v23, v23 quad_perm:[3,2,1,0] row_mask:0xf bank_mask:0xf
	s_and_saveexec_b64 s[2:3], s[12:13]
	s_xor_b64 s[18:19], exec, s[2:3]
	s_cbranch_execz .LBB0_314
	s_and_saveexec_b64 s[30:31], s[14:15]
	s_cbranch_execz .LBB0_189
	ds_read_b128 v[68:71], v49
	s_waitcnt lgkmcnt(0)
	v_pk_mul_f32 v[72:73], v[20:21], v[68:69]
	v_mul_f32_e32 v20, v69, v22
	v_mov_b32_e32 v22, v21
	v_pk_mul_f32 v[22:23], v[70:71], v[22:23]
	s_nop 0
	v_mov_b32_e32 v73, v22
	v_mov_b32_e32 v21, v23
	v_pk_add_f32 v[20:21], v[72:73], v[20:21]

; DI unsigned pk2(float lo, float hi) { f32x2 x = {lo, hi}; return __builtin_bit_cast(unsigned, __builtin_convertvector(x, bf16x2_t)); }
; DI float sum16(float v) { v += __shfl_xor(v, 8); v += __shfl_xor(v, 4); v += __shfl_xor(v, 2); v += __shfl_xor(v, 1); return v; }
; DI void post_unit(const Params& p, int l, int unit, LAS unsigned char* lds) {
;     ...
;       } else if (s < 12) {
;         rope2<16>(x, hl, cs64 + t * 32);
;         const int hd = ((s & 1) ? 2 : 0) + hsel;
;         const float lg = log1pf(-exp2f(-5.0f - (float)hd));
;         const float f = (s < 10) ? expf(lg * (float)(t + 1)) : expf(lg * (float)(63 - t)) * 0.125f;
;         x *= f; *(unsigned*)pp = pk2(x[0], x[1]);
;       } else {
;         const float* gn = (s < 14) ? qnc : knc;
;         const float rs = rsqrtf(sum16(x[0] * x[0] + x[1] * x[1]) * (1.0f / 32.0f) + EPS);
;         x[0] *= rs * gn[2 * hl16]; x[1] *= rs * gn[2 * hl16 + 1]; rope2<2>(x, hl16, cs8 + t * 4);
;         if (s < 14) x *= LOG2E * 0.17677669529663687f;
;         *(unsigned*)pp = pk2(x[0], x[1]);
.LBB0_208:
	s_or_b64 exec, exec, s[18:19]
	s_waitcnt lgkmcnt(1)
	v_mul_f32_e32 v64, v32, v65
	v_mul_f32_e32 v65, 0x3fb8aa3b, v64
	v_fma_f32 v66, v64, s64, -v65
	v_rndne_f32_e32 v67, v65
	v_fmac_f32_e32 v66, 0x32a5705f, v64
	v_sub_f32_e32 v65, v65, v67
	v_add_f32_e32 v65, v65, v66
	v_exp_f32_e32 v65, v65
	v_cvt_i32_f32_e32 v66, v67
	v_cmp_ngt_f32_e32 vcc, s65, v64
	s_mov_b64 s[2:3], 0xa000c80
	s_waitcnt lgkmcnt(0)
	v_lshl_add_u64 v[20:21], v[18:19], 0, s[2:3]
	v_ldexp_f32 v65, v65, v66
	v_cndmask_b32_e32 v65, 0, v65, vcc
	v_cmp_nlt_f32_e32 vcc, s89, v64
	s_nop 1
	v_cndmask_b32_e32 v64, v177, v65, vcc
	v_mul_f32_e32 v64, 0x3e000000, v64
	v_pk_mul_f32 v[22:23], v[64:65], v[22:23] op_sel_hi:[0,1]
	v_cvt_pk_bf16_f32 v22, v22, v23
	global_store_dword v[20:21], v22, off
	s_waitcnt vmcnt(29)
	v_lshlrev_b32_e32 v20, 16, v54
	v_and_b32_e32 v21, 0xffff0000, v54
	v_pk_mul_f32 v[22:23], v[20:21], v[20:21]
	s_nop 0
	v_add_f32_e32 v22, v22, v23
	s_nop 1
	v_add_f32_dpp v22, v22, v22 row_ror:8 row_mask:0xf bank_mask:0xf
	s_nop 1
	v_add_f32_dpp v22, v22, v22 row_ror:4 row_mask:0xf bank_mask:0xf
	s_nop 1
	v_add_f32_dpp v22, v22, v22 quad_perm:[2,3,0,1] row_mask:0xf bank_mask:0xf
	s_nop 1
	v_add_f32_dpp v22, v22, v22 quad_perm:[1,0,3,2] row_mask:0xf bank_mask:0xf
	v_fmamk_f32 v22, v22, 0x3d000000, v170
	v_cmp_gt_f32_e32 vcc, s33, v22
	v_mul_f32_e32 v23, 0x4b800000, v22
	s_nop 0
	v_cndmask_b32_e32 v22, v22, v23, vcc
	v_rsq_f32_e32 v22, v22
	s_nop 0
	v_mul_f32_e32 v23, 0x45800000, v22
	v_cndmask_b32_e32 v22, v22, v23, vcc
	v_pk_mul_f32 v[22:23], v[6:7], v[22:23] op_sel_hi:[1,0]
	s_nop 0
	v_pk_mul_f32 v[22:23], v[22:23], v[20:21]
	s_nop 1
	v_mov_b32_dpp v20, v22 quad_perm:[2,3,0,1] row_mask:0xf bank_mask:0xf
	v_mov_b32_dpp v21, v23 quad_perm:[2,3,0,1] row_mask:0xf bank_mask:0xf
	s_and_saveexec_b64 s[2:3], s[6:7]
	s_xor_b64 s[18:19], exec, s[2:3]
	s_cbranch_execz .LBB0_212
	s_and_saveexec_b64 s[30:31], s[8:9]
	s_cbranch_execz .LBB0_211
	v_add_u32_e32 v54, 0, v40
	ds_read_b128 v[64:67], v54
	s_waitcnt lgkmcnt(0)
	v_pk_mul_f32 v[68:69], v[22:23], v[64:65]
	v_mul_f32_e32 v22, v65, v20
	v_mov_b32_e32 v20, v23
	v_pk_mul_f32 v[20:21], v[20:21], v[66:67]
	s_nop 0
	v_mov_b32_e32 v69, v20
	v_mov_b32_e32 v23, v21
	v_pk_add_f32 v[22:23], v[68:69], v[22:23]

; DI unsigned pk2(float lo, float hi) { f32x2 x = {lo, hi}; return __builtin_bit_cast(unsigned, __builtin_convertvector(x, bf16x2_t)); }
; DI float sum16(float v) { v += __shfl_xor(v, 8); v += __shfl_xor(v, 4); v += __shfl_xor(v, 2); v += __shfl_xor(v, 1); return v; }
; DI void post_unit(const Params& p, int l, int unit, LAS unsigned char* lds) {
;     ...
;       } else {
;         const float* gn = (s < 14) ? qnc : knc;
;         const float rs = rsqrtf(sum16(x[0] * x[0] + x[1] * x[1]) * (1.0f / 32.0f) + EPS);
;         x[0] *= rs * gn[2 * hl16]; x[1] *= rs * gn[2 * hl16 + 1]; rope2<2>(x, hl16, cs8 + t * 4);
;         if (s < 14) x *= LOG2E * 0.17677669529663687f;
;         *(unsigned*)pp = pk2(x[0], x[1]);
.LBB0_214:
	s_or_b64 exec, exec, s[18:19]
	s_mov_b64 s[2:3], 0xa001180
	s_waitcnt lgkmcnt(0)
	v_lshl_add_u64 v[20:21], v[18:19], 0, s[2:3]
	s_mov_b32 s2, 0x3e8293ee
	v_pk_mul_f32 v[22:23], v[22:23], s[2:3] op_sel_hi:[1,0]
	s_nop 0
	v_cvt_pk_bf16_f32 v22, v22, v23
	global_store_dword v[20:21], v22, off
	s_waitcnt vmcnt(29)
	v_lshlrev_b32_e32 v20, 16, v63
	v_and_b32_e32 v21, 0xffff0000, v63
	v_pk_mul_f32 v[22:23], v[20:21], v[20:21]
	s_nop 0
	v_add_f32_e32 v22, v22, v23
	s_nop 1
	v_add_f32_dpp v22, v22, v22 row_ror:8 row_mask:0xf bank_mask:0xf
	s_nop 1
	v_add_f32_dpp v22, v22, v22 row_ror:4 row_mask:0xf bank_mask:0xf
	s_nop 1
	v_add_f32_dpp v22, v22, v22 quad_perm:[2,3,0,1] row_mask:0xf bank_mask:0xf
	s_nop 1
	v_add_f32_dpp v22, v22, v22 quad_perm:[1,0,3,2] row_mask:0xf bank_mask:0xf
	v_fmamk_f32 v22, v22, 0x3d000000, v170
	v_cmp_gt_f32_e32 vcc, s33, v22
	v_mul_f32_e32 v23, 0x4b800000, v22
	s_nop 0
	v_cndmask_b32_e32 v22, v22, v23, vcc
	v_rsq_f32_e32 v22, v22
	s_nop 0
	v_mul_f32_e32 v23, 0x45800000, v22
	v_cndmask_b32_e32 v22, v22, v23, vcc
	v_pk_mul_f32 v[22:23], v[6:7], v[22:23] op_sel_hi:[1,0]
	s_nop 0
	v_pk_mul_f32 v[22:23], v[22:23], v[20:21]
	s_nop 1
	v_mov_b32_dpp v20, v22 quad_perm:[2,3,0,1] row_mask:0xf bank_mask:0xf
	v_mov_b32_dpp v21, v23 quad_perm:[2,3,0,1] row_mask:0xf bank_mask:0xf
	s_and_saveexec_b64 s[2:3], s[6:7]
	s_xor_b64 s[18:19], exec, s[2:3]
	s_cbranch_execz .LBB0_218
	s_and_saveexec_b64 s[30:31], s[8:9]
	s_cbranch_execz .LBB0_217
	ds_read_b128 v[64:67], v54
	s_waitcnt lgkmcnt(0)
	v_pk_mul_f32 v[68:69], v[22:23], v[64:65]
	v_mul_f32_e32 v22, v65, v20
	v_mov_b32_e32 v20, v23
	v_pk_mul_f32 v[20:21], v[20:21], v[66:67]
	s_nop 0
	v_mov_b32_e32 v69, v20
	v_mov_b32_e32 v23, v21
	v_pk_add_f32 v[22:23], v[68:69], v[22:23]

; DI unsigned pk2(float lo, float hi) { f32x2 x = {lo, hi}; return __builtin_bit_cast(unsigned, __builtin_convertvector(x, bf16x2_t)); }
; DI float sum16(float v) { v += __shfl_xor(v, 8); v += __shfl_xor(v, 4); v += __shfl_xor(v, 2); v += __shfl_xor(v, 1); return v; }
; DI void post_unit(const Params& p, int l, int unit, LAS unsigned char* lds) {
;     ...
;       } else {
;         const float* gn = (s < 14) ? qnc : knc;
;         const float rs = rsqrtf(sum16(x[0] * x[0] + x[1] * x[1]) * (1.0f / 32.0f) + EPS);
;         x[0] *= rs * gn[2 * hl16]; x[1] *= rs * gn[2 * hl16 + 1]; rope2<2>(x, hl16, cs8 + t * 4);
;         if (s < 14) x *= LOG2E * 0.17677669529663687f;
;         *(unsigned*)pp = pk2(x[0], x[1]);
.LBB0_220:
	s_or_b64 exec, exec, s[18:19]
	s_mov_b64 s[2:3], 0xa001280
	s_waitcnt lgkmcnt(0)
	v_lshl_add_u64 v[20:21], v[18:19], 0, s[2:3]
	s_mov_b32 s2, 0x3e8293ee
	v_pk_mul_f32 v[22:23], v[22:23], s[2:3] op_sel_hi:[1,0]
	s_nop 0
	v_cvt_pk_bf16_f32 v22, v22, v23
	global_store_dword v[20:21], v22, off
	s_waitcnt vmcnt(29)
	v_lshlrev_b32_e32 v20, 16, v62
	v_and_b32_e32 v21, 0xffff0000, v62
	v_pk_mul_f32 v[22:23], v[20:21], v[20:21]
	s_nop 0
	v_add_f32_e32 v22, v22, v23
	s_nop 1
	v_add_f32_dpp v22, v22, v22 row_ror:8 row_mask:0xf bank_mask:0xf
	s_nop 1
	v_add_f32_dpp v22, v22, v22 row_ror:4 row_mask:0xf bank_mask:0xf
	s_nop 1
	v_add_f32_dpp v22, v22, v22 quad_perm:[2,3,0,1] row_mask:0xf bank_mask:0xf
	s_nop 1
	v_add_f32_dpp v22, v22, v22 quad_perm:[1,0,3,2] row_mask:0xf bank_mask:0xf
	v_fmamk_f32 v22, v22, 0x3d000000, v170
	v_cmp_gt_f32_e32 vcc, s33, v22
	v_mul_f32_e32 v23, 0x4b800000, v22
	s_nop 0
	v_cndmask_b32_e32 v22, v22, v23, vcc
	v_rsq_f32_e32 v22, v22
	s_nop 0
	v_mul_f32_e32 v23, 0x45800000, v22
	v_cndmask_b32_e32 v22, v22, v23, vcc
	v_pk_mul_f32 v[22:23], v[8:9], v[22:23] op_sel_hi:[1,0]
	s_nop 0
	v_pk_mul_f32 v[22:23], v[22:23], v[20:21]
	s_nop 1
	v_mov_b32_dpp v20, v22 quad_perm:[2,3,0,1] row_mask:0xf bank_mask:0xf
	v_mov_b32_dpp v21, v23 quad_perm:[2,3,0,1] row_mask:0xf bank_mask:0xf
	s_and_saveexec_b64 s[2:3], s[6:7]
	s_xor_b64 s[18:19], exec, s[2:3]
	s_cbranch_execz .LBB0_224
	s_and_saveexec_b64 s[30:31], s[8:9]
	s_cbranch_execz .LBB0_223
	ds_read_b128 v[62:65], v54
	s_waitcnt lgkmcnt(0)
	v_pk_mul_f32 v[66:67], v[22:23], v[62:63]
	v_mul_f32_e32 v22, v63, v20
	v_mov_b32_e32 v20, v23
	v_pk_mul_f32 v[20:21], v[20:21], v[64:65]
	s_nop 0
	v_mov_b32_e32 v67, v20
	v_mov_b32_e32 v23, v21
	v_pk_add_f32 v[22:23], v[66:67], v[22:23]

; DI unsigned pk2(float lo, float hi) { f32x2 x = {lo, hi}; return __builtin_bit_cast(unsigned, __builtin_convertvector(x, bf16x2_t)); }
; DI float sum16(float v) { v += __shfl_xor(v, 8); v += __shfl_xor(v, 4); v += __shfl_xor(v, 2); v += __shfl_xor(v, 1); return v; }
; DI void post_unit(const Params& p, int l, int unit, LAS unsigned char* lds) {
;     ...
;       } else {
;         const float* gn = (s < 14) ? qnc : knc;
;         const float rs = rsqrtf(sum16(x[0] * x[0] + x[1] * x[1]) * (1.0f / 32.0f) + EPS);
;         x[0] *= rs * gn[2 * hl16]; x[1] *= rs * gn[2 * hl16 + 1]; rope2<2>(x, hl16, cs8 + t * 4);
;         if (s < 14) x *= LOG2E * 0.17677669529663687f;
;         *(unsigned*)pp = pk2(x[0], x[1]);
.LBB0_226:
	s_or_b64 exec, exec, s[18:19]
	s_mov_b64 s[2:3], 0xa001380
	s_waitcnt lgkmcnt(0)
	v_lshl_add_u64 v[20:21], v[18:19], 0, s[2:3]
	v_cvt_pk_bf16_f32 v22, v22, v23
	global_store_dword v[20:21], v22, off
	s_waitcnt vmcnt(29)
	v_lshlrev_b32_e32 v20, 16, v61
	v_and_b32_e32 v21, 0xffff0000, v61
	v_pk_mul_f32 v[22:23], v[20:21], v[20:21]
	s_nop 0
	v_add_f32_e32 v22, v22, v23
	s_nop 1
	v_add_f32_dpp v22, v22, v22 row_ror:8 row_mask:0xf bank_mask:0xf
	s_nop 1
	v_add_f32_dpp v22, v22, v22 row_ror:4 row_mask:0xf bank_mask:0xf
	s_nop 1
	v_add_f32_dpp v22, v22, v22 quad_perm:[2,3,0,1] row_mask:0xf bank_mask:0xf
	s_nop 1
	v_add_f32_dpp v22, v22, v22 quad_perm:[1,0,3,2] row_mask:0xf bank_mask:0xf
	v_fmamk_f32 v22, v22, 0x3d000000, v170
	v_cmp_gt_f32_e32 vcc, s33, v22
	v_mul_f32_e32 v23, 0x4b800000, v22
	s_nop 0
	v_cndmask_b32_e32 v22, v22, v23, vcc
	v_rsq_f32_e32 v22, v22
	s_nop 0
	v_mul_f32_e32 v23, 0x45800000, v22
	v_cndmask_b32_e32 v22, v22, v23, vcc
	v_pk_mul_f32 v[22:23], v[8:9], v[22:23] op_sel_hi:[1,0]
	s_nop 0
	v_pk_mul_f32 v[22:23], v[22:23], v[20:21]
	s_nop 1
	v_mov_b32_dpp v20, v22 quad_perm:[2,3,0,1] row_mask:0xf bank_mask:0xf
	v_mov_b32_dpp v21, v23 quad_perm:[2,3,0,1] row_mask:0xf bank_mask:0xf
	s_and_saveexec_b64 s[2:3], s[6:7]
	s_xor_b64 s[18:19], exec, s[2:3]
	s_cbranch_execz .LBB0_230
	s_and_saveexec_b64 s[30:31], s[8:9]
	s_cbranch_execz .LBB0_229
	ds_read_b128 v[62:65], v54
	s_waitcnt lgkmcnt(0)
	v_pk_mul_f32 v[66:67], v[22:23], v[62:63]
	v_mul_f32_e32 v22, v63, v20
	v_mov_b32_e32 v20, v23
	v_pk_mul_f32 v[20:21], v[20:21], v[64:65]
	s_nop 0
	v_mov_b32_e32 v67, v20
	v_mov_b32_e32 v23, v21
	v_pk_add_f32 v[22:23], v[66:67], v[22:23]

; DI float sum32(float v) { v += __shfl_xor(v, 16); return sum16(v); }
; DI f32x2 unpk(unsigned w) { f32x2 r = {bflo(w), bfhi(w)}; return r; }
; DI void post_unit(const Params& p, int l, int unit, LAS unsigned char* lds) {
;     ...
;     for (int hf = 0; hf < 2; ++hf) {
;     const int t = w * 8 + 2 * tp + hf; u16* row = proj + (tok0 + t) * NP;
; #pragma unroll
;     for (int s = 0; s < 16; ++s) {
;       f32x2 x = unpk(raw2[hf][s]); u16* pp = row + segcol[s] + 2 * lane;
;       if (s < 2) {
;         const float rs = rsqrtf(sum32(x[0] * x[0] + x[1] * x[1]) * (1.0f / 64.0f) + EPS);
;         x[0] *= rs * qna[2 * hl]; x[1] *= rs * qna[2 * hl + 1]; rope2<4>(x, hl, cs16 + t * 8);
.LBB0_232:
	s_or_b64 exec, exec, s[18:19]
	s_mov_b64 s[2:3], 0xa001480
	v_lshl_add_u64 v[18:19], v[18:19], 0, s[2:3]
	s_waitcnt lgkmcnt(1)
	v_cvt_pk_bf16_f32 v20, v22, v23
	global_store_dword v[18:19], v20, off
	s_waitcnt vmcnt(29)
	v_and_b32_e32 v19, 0xffff0000, v60
	v_lshlrev_b32_e32 v18, 16, v60
	s_waitcnt lgkmcnt(0)
	v_pk_mul_f32 v[20:21], v[18:19], v[18:19]
	s_nop 0
	v_add_f32_e32 v20, v20, v21
	v_mov_b32_e32 v21, v20
	s_nop 1
	v_permlane16_swap_b32_e32 v20, v21
	v_add_f32_e32 v20, v20, v21
	s_nop 1
	v_add_f32_dpp v20, v20, v20 row_ror:8 row_mask:0xf bank_mask:0xf
	s_nop 1
	v_add_f32_dpp v20, v20, v20 row_ror:4 row_mask:0xf bank_mask:0xf
	s_nop 1
	v_add_f32_dpp v20, v20, v20 quad_perm:[2,3,0,1] row_mask:0xf bank_mask:0xf
	s_nop 1
	v_add_f32_dpp v20, v20, v20 quad_perm:[1,0,3,2] row_mask:0xf bank_mask:0xf
	v_fmamk_f32 v20, v20, 0x3c800000, v170
	v_cmp_gt_f32_e32 vcc, s33, v20
	v_mul_f32_e32 v21, 0x4b800000, v20
	s_nop 0
	v_cndmask_b32_e32 v20, v20, v21, vcc
	v_rsq_f32_e32 v20, v20
	s_nop 0
	v_mul_f32_e32 v21, 0x45800000, v20
	v_cndmask_b32_e32 v20, v20, v21, vcc
	v_pk_mul_f32 v[20:21], v[4:5], v[20:21] op_sel_hi:[1,0]
	s_nop 0
	v_pk_mul_f32 v[20:21], v[20:21], v[18:19]
	s_nop 1
	v_mov_b32_dpp v18, v20 row_half_mirror row_mask:0xf bank_mask:0xf
	v_mov_b32_dpp v19, v21 row_half_mirror row_mask:0xf bank_mask:0xf
	s_nop 0
	v_mov_b32_dpp v18, v18 quad_perm:[3,2,1,0] row_mask:0xf bank_mask:0xf
	v_mov_b32_dpp v19, v19 quad_perm:[3,2,1,0] row_mask:0xf bank_mask:0xf
	s_and_saveexec_b64 s[2:3], s[12:13]
	s_xor_b64 s[18:19], exec, s[2:3]
	s_cbranch_execz .LBB0_236
	s_and_saveexec_b64 s[30:31], s[14:15]
	s_cbranch_execz .LBB0_235
	ds_read_b128 v[60:63], v49 offset:64
	s_waitcnt lgkmcnt(0)
	v_pk_mul_f32 v[22:23], v[20:21], v[60:61]
	v_mul_f32_e32 v20, v61, v18
	v_mov_b32_e32 v18, v21
	v_pk_mul_f32 v[18:19], v[18:19], v[62:63]
	s_nop 0
	v_mov_b32_e32 v23, v18
	v_mov_b32_e32 v21, v19
	v_pk_add_f32 v[20:21], v[22:23], v[20:21]

; #define LAS __attribute__((address_space(3)))
; DI unsigned pk2(float lo, float hi) { f32x2 x = {lo, hi}; return __builtin_bit_cast(unsigned, __builtin_convertvector(x, bf16x2_t)); }
; DI float sum32(float v) { v += __shfl_xor(v, 16); return sum16(v); }
; DI f32x2 unpk(unsigned w) { f32x2 r = {bflo(w), bfhi(w)}; return r; }
; template <int HP> DI void rope2(f32x2& x, int hl, const LAS f32x2* cs) {
;   const float pa = __shfl_xor(x[0], HP), pb = __shfl_xor(x[1], HP);
;   if (hl < HP) { const f32x2 c0 = cs[2 * hl], c1 = cs[2 * hl + 1]; x[0] = x[0] * c0[0] - pa * c0[1]; x[1] = x[1] * c1[0] - pb * c1[1]; }
;   else if (hl < 2 * HP) { const f32x2 c0 = cs[2 * (hl - HP)], c1 = cs[2 * (hl - HP) + 1]; x[0] = x[0] * c0[0] + pa * c0[1]; x[1] = x[1] * c1[0] + pb * c1[1]; }
; DI void post_unit(const Params& p, int l, int unit, LAS unsigned char* lds) {
;     ...
;       f32x2 x = unpk(raw2[hf][s]); u16* pp = row + segcol[s] + 2 * lane;
;       if (s < 2) {
;         const float rs = rsqrtf(sum32(x[0] * x[0] + x[1] * x[1]) * (1.0f / 64.0f) + EPS);
;         x[0] *= rs * qna[2 * hl]; x[1] *= rs * qna[2 * hl + 1]; rope2<4>(x, hl, cs16 + t * 8);
;         x *= LOG2E * 0.125f; *(unsigned*)pp = pk2(x[0], x[1]);
.LBB0_238:
	s_or_b64 exec, exec, s[18:19]
	s_mov_b32 s2, 0x3e38aa3b
	s_waitcnt lgkmcnt(0)
	v_lshl_add_u64 v[18:19], v[14:15], 0, v[0:1]
	v_pk_mul_f32 v[20:21], v[20:21], s[2:3] op_sel_hi:[1,0]
	s_nop 0
	v_cvt_pk_bf16_f32 v22, v20, v21
	v_add_co_u32_e32 v20, vcc, 0xa002000, v18
	s_nop 1
	v_addc_co_u32_e32 v21, vcc, 0, v19, vcc
	global_store_dword v[20:21], v22, off offset:512
	s_waitcnt vmcnt(29)
	v_and_b32_e32 v21, 0xffff0000, v57
	v_lshlrev_b32_e32 v20, 16, v57
	v_pk_mul_f32 v[22:23], v[20:21], v[20:21]
	s_nop 0
	v_add_f32_e32 v22, v22, v23
	v_mov_b32_e32 v23, v22
	s_nop 1
	v_permlane16_swap_b32_e32 v22, v23
	v_add_f32_e32 v22, v22, v23
	s_nop 1
	v_add_f32_dpp v22, v22, v22 row_ror:8 row_mask:0xf bank_mask:0xf
	s_nop 1
	v_add_f32_dpp v22, v22, v22 row_ror:4 row_mask:0xf bank_mask:0xf
	s_nop 1
	v_add_f32_dpp v22, v22, v22 quad_perm:[2,3,0,1] row_mask:0xf bank_mask:0xf
	s_nop 1
	v_add_f32_dpp v22, v22, v22 quad_perm:[1,0,3,2] row_mask:0xf bank_mask:0xf
	v_fmamk_f32 v22, v22, 0x3c800000, v170
	v_cmp_gt_f32_e32 vcc, s33, v22
	v_mul_f32_e32 v23, 0x4b800000, v22
	s_nop 0
	v_cndmask_b32_e32 v22, v22, v23, vcc
	v_rsq_f32_e32 v22, v22
	s_nop 0
	v_mul_f32_e32 v23, 0x45800000, v22
	v_cndmask_b32_e32 v22, v22, v23, vcc
	v_pk_mul_f32 v[22:23], v[4:5], v[22:23] op_sel_hi:[1,0]
	s_nop 0
	v_pk_mul_f32 v[22:23], v[22:23], v[20:21]
	s_nop 1
	v_mov_b32_dpp v20, v22 row_half_mirror row_mask:0xf bank_mask:0xf
	v_mov_b32_dpp v21, v23 row_half_mirror row_mask:0xf bank_mask:0xf
	s_nop 0
	v_mov_b32_dpp v20, v20 quad_perm:[3,2,1,0] row_mask:0xf bank_mask:0xf
	v_mov_b32_dpp v21, v21 quad_perm:[3,2,1,0] row_mask:0xf bank_mask:0xf
	s_and_saveexec_b64 s[2:3], s[12:13]
	s_xor_b64 s[18:19], exec, s[2:3]
	s_cbranch_execz .LBB0_242
	s_and_saveexec_b64 s[30:31], s[14:15]
	s_cbranch_execz .LBB0_241
	ds_read_b128 v[60:63], v49 offset:64
	s_waitcnt lgkmcnt(0)
	v_pk_mul_f32 v[64:65], v[22:23], v[60:61]
	v_mul_f32_e32 v22, v61, v20
	v_mov_b32_e32 v20, v23
	v_pk_mul_f32 v[20:21], v[20:21], v[62:63]
	s_nop 0
	v_mov_b32_e32 v65, v20
	v_mov_b32_e32 v23, v21
	v_pk_add_f32 v[22:23], v[64:65], v[22:23]

; #define LAS __attribute__((address_space(3)))
; DI unsigned pk2(float lo, float hi) { f32x2 x = {lo, hi}; return __builtin_bit_cast(unsigned, __builtin_convertvector(x, bf16x2_t)); }
; DI float sum32(float v) { v += __shfl_xor(v, 16); return sum16(v); }
; DI float sum64(float v) { v += __shfl_xor(v, 32); return sum32(v); }
; DI f32x2 unpk(unsigned w) { f32x2 r = {bflo(w), bfhi(w)}; return r; }
; template <int HP> DI void rope2(f32x2& x, int hl, const LAS f32x2* cs) {
;   const float pa = __shfl_xor(x[0], HP), pb = __shfl_xor(x[1], HP);
;   if (hl < HP) { const f32x2 c0 = cs[2 * hl], c1 = cs[2 * hl + 1]; x[0] = x[0] * c0[0] - pa * c0[1]; x[1] = x[1] * c1[0] - pb * c1[1]; }
;   else if (hl < 2 * HP) { const f32x2 c0 = cs[2 * (hl - HP)], c1 = cs[2 * (hl - HP) + 1]; x[0] = x[0] * c0[0] + pa * c0[1]; x[1] = x[1] * c1[0] + pb * c1[1]; }
; DI void post_unit(const Params& p, int l, int unit, LAS unsigned char* lds) {
;     ...
;       f32x2 x = unpk(raw2[hf][s]); u16* pp = row + segcol[s] + 2 * lane;
;       if (s < 2) {
;         const float rs = rsqrtf(sum32(x[0] * x[0] + x[1] * x[1]) * (1.0f / 64.0f) + EPS);
;         x[0] *= rs * qna[2 * hl]; x[1] *= rs * qna[2 * hl + 1]; rope2<4>(x, hl, cs16 + t * 8);
;         x *= LOG2E * 0.125f; *(unsigned*)pp = pk2(x[0], x[1]);
;       } else if (s == 2) {
;         const float rs = rsqrtf(sum64(x[0] * x[0] + x[1] * x[1]) * (1.0f / 128.0f) + EPS);
;         *(LAS unsigned*)(At + t * 272 + lane * 4) = pk2(x[0] * rs, x[1] * rs);
;       } else if (s < 7) {
;         rope2<4>(x, hl, cs16 + t * 8); *(unsigned*)pp = pk2(x[0], x[1]);
.LBB0_244:
	s_or_b64 exec, exec, s[18:19]
	s_mov_b32 s2, 0x3e38aa3b
	s_waitcnt lgkmcnt(0)
	v_pk_mul_f32 v[20:21], v[22:23], s[2:3] op_sel_hi:[1,0]
	s_nop 0
	v_cvt_pk_bf16_f32 v22, v20, v21
	v_add_co_u32_e32 v20, vcc, 0xa002000, v18
	s_nop 1
	v_addc_co_u32_e32 v21, vcc, 0, v19, vcc
	global_store_dword v[20:21], v22, off offset:768
	s_waitcnt vmcnt(29)
	v_lshlrev_b32_e32 v20, 16, v55
	v_and_b32_e32 v21, 0xffff0000, v55
	v_pk_mul_f32 v[22:23], v[20:21], v[20:21]
	s_nop 0
	v_add_f32_e32 v22, v22, v23
	v_mov_b32_e32 v23, v22
	s_nop 1
	v_permlane32_swap_b32_e32 v22, v23
	v_add_f32_e32 v22, v22, v23
	v_mov_b32_e32 v23, v22
	s_nop 1
	v_permlane16_swap_b32_e32 v22, v23
	v_add_f32_e32 v22, v22, v23
	s_nop 1
	v_add_f32_dpp v22, v22, v22 row_ror:8 row_mask:0xf bank_mask:0xf
	s_nop 1
	v_add_f32_dpp v22, v22, v22 row_ror:4 row_mask:0xf bank_mask:0xf
	s_nop 1
	v_add_f32_dpp v22, v22, v22 quad_perm:[2,3,0,1] row_mask:0xf bank_mask:0xf
	s_nop 1
	v_add_f32_dpp v22, v22, v22 quad_perm:[1,0,3,2] row_mask:0xf bank_mask:0xf
	v_fmamk_f32 v22, v22, 0x3c000000, v170
	v_cmp_gt_f32_e32 vcc, s33, v22
	v_mul_f32_e32 v23, 0x4b800000, v22
	s_nop 0
	v_cndmask_b32_e32 v22, v22, v23, vcc
	v_rsq_f32_e32 v22, v22
	s_nop 0
	v_mul_f32_e32 v23, 0x45800000, v22
	v_cndmask_b32_e32 v22, v22, v23, vcc
	v_pk_mul_f32 v[20:21], v[22:23], v[20:21] op_sel_hi:[0,1]
	v_cvt_pk_bf16_f32 v20, v20, v21
	ds_write_b32 v59, v20 offset:272
	s_waitcnt vmcnt(28)
	v_lshlrev_b32_e32 v20, 16, v53
	v_and_b32_e32 v21, 0xffff0000, v53
	s_nop 1
	v_mov_b32_dpp v53, v20 row_half_mirror row_mask:0xf bank_mask:0xf
	v_mov_b32_dpp v23, v21 row_half_mirror row_mask:0xf bank_mask:0xf
	s_nop 0
	v_mov_b32_dpp v53, v53 quad_perm:[3,2,1,0] row_mask:0xf bank_mask:0xf
	v_mov_b32_dpp v23, v23 quad_perm:[3,2,1,0] row_mask:0xf bank_mask:0xf
	s_and_saveexec_b64 s[2:3], s[12:13]
	s_xor_b64 s[18:19], exec, s[2:3]
	s_cbranch_execz .LBB0_248
	s_and_saveexec_b64 s[30:31], s[14:15]
	s_cbranch_execz .LBB0_247
	ds_read_b128 v[60:63], v49 offset:64
	v_mov_b32_e32 v22, v21
	s_waitcnt lgkmcnt(0)
	v_pk_mul_f32 v[22:23], v[62:63], v[22:23]
	v_mul_f32_e32 v20, v60, v20
	v_mul_f32_e32 v60, v61, v53
	v_mov_b32_e32 v21, v22
	v_mov_b32_e32 v61, v23
	v_pk_add_f32 v[20:21], v[20:21], v[60:61]

; #define LAS __attribute__((address_space(3)))
; DI unsigned pk2(float lo, float hi) { f32x2 x = {lo, hi}; return __builtin_bit_cast(unsigned, __builtin_convertvector(x, bf16x2_t)); }
; template <int HP> DI void rope2(f32x2& x, int hl, const LAS f32x2* cs) {
;   const float pa = __shfl_xor(x[0], HP), pb = __shfl_xor(x[1], HP);
;   if (hl < HP) { const f32x2 c0 = cs[2 * hl], c1 = cs[2 * hl + 1]; x[0] = x[0] * c0[0] - pa * c0[1]; x[1] = x[1] * c1[0] - pb * c1[1]; }
;   else if (hl < 2 * HP) { const f32x2 c0 = cs[2 * (hl - HP)], c1 = cs[2 * (hl - HP) + 1]; x[0] = x[0] * c0[0] + pa * c0[1]; x[1] = x[1] * c1[0] + pb * c1[1]; }
; DI void post_unit(const Params& p, int l, int unit, LAS unsigned char* lds) {
;     ...
;       } else if (s < 7) {
;         rope2<4>(x, hl, cs16 + t * 8); *(unsigned*)pp = pk2(x[0], x[1]);
.LBB0_250:
	s_or_b64 exec, exec, s[18:19]
	v_cvt_pk_bf16_f32 v22, v20, v21
	v_add_co_u32_e32 v20, vcc, 0xa002000, v18
	s_nop 1
	v_addc_co_u32_e32 v21, vcc, 0, v19, vcc
	global_store_dword v[20:21], v22, off offset:1280
	s_waitcnt vmcnt(28)
	v_lshlrev_b32_e32 v20, 16, v52
	v_and_b32_e32 v21, 0xffff0000, v52
	s_nop 1
	v_mov_b32_dpp v52, v20 row_half_mirror row_mask:0xf bank_mask:0xf
	s_nop 1
	v_mov_b32_dpp v52, v52 quad_perm:[3,2,1,0] row_mask:0xf bank_mask:0xf
	s_waitcnt lgkmcnt(1)
	s_nop 1
	v_mov_b32_dpp v23, v21 row_half_mirror row_mask:0xf bank_mask:0xf
	s_nop 1
	v_mov_b32_dpp v23, v23 quad_perm:[3,2,1,0] row_mask:0xf bank_mask:0xf
	s_and_saveexec_b64 s[2:3], s[12:13]
	s_xor_b64 s[18:19], exec, s[2:3]
	s_cbranch_execz .LBB0_254
	s_and_saveexec_b64 s[30:31], s[14:15]
	s_cbranch_execz .LBB0_253
	ds_read_b128 v[60:63], v49 offset:64
	v_mov_b32_e32 v22, v21
	s_waitcnt lgkmcnt(0)
	v_pk_mul_f32 v[22:23], v[62:63], v[22:23]
	v_mul_f32_e32 v20, v60, v20
	v_mul_f32_e32 v52, v61, v52
	v_mov_b32_e32 v21, v22
	v_mov_b32_e32 v53, v23
	v_pk_add_f32 v[20:21], v[20:21], v[52:53]

; #define LAS __attribute__((address_space(3)))
; DI unsigned pk2(float lo, float hi) { f32x2 x = {lo, hi}; return __builtin_bit_cast(unsigned, __builtin_convertvector(x, bf16x2_t)); }
; template <int HP> DI void rope2(f32x2& x, int hl, const LAS f32x2* cs) {
;   const float pa = __shfl_xor(x[0], HP), pb = __shfl_xor(x[1], HP);
;   if (hl < HP) { const f32x2 c0 = cs[2 * hl], c1 = cs[2 * hl + 1]; x[0] = x[0] * c0[0] - pa * c0[1]; x[1] = x[1] * c1[0] - pb * c1[1]; }
;   else if (hl < 2 * HP) { const f32x2 c0 = cs[2 * (hl - HP)], c1 = cs[2 * (hl - HP) + 1]; x[0] = x[0] * c0[0] + pa * c0[1]; x[1] = x[1] * c1[0] + pb * c1[1]; }
; DI void post_unit(const Params& p, int l, int unit, LAS unsigned char* lds) {
;     ...
;       } else if (s < 7) {
;         rope2<4>(x, hl, cs16 + t * 8); *(unsigned*)pp = pk2(x[0], x[1]);
.LBB0_256:
	s_or_b64 exec, exec, s[18:19]
	v_cvt_pk_bf16_f32 v22, v20, v21
	v_add_co_u32_e32 v20, vcc, 0xa002000, v18
	s_nop 1
	v_addc_co_u32_e32 v21, vcc, 0, v19, vcc
	global_store_dword v[20:21], v22, off offset:1536
	s_waitcnt vmcnt(28)
	v_lshlrev_b32_e32 v20, 16, v51
	v_and_b32_e32 v21, 0xffff0000, v51
	s_nop 1
	v_mov_b32_dpp v51, v20 row_half_mirror row_mask:0xf bank_mask:0xf
	s_nop 1
	v_mov_b32_dpp v51, v51 quad_perm:[3,2,1,0] row_mask:0xf bank_mask:0xf
	s_waitcnt lgkmcnt(1)
	s_nop 1
	v_mov_b32_dpp v23, v21 row_half_mirror row_mask:0xf bank_mask:0xf
	s_nop 1
	v_mov_b32_dpp v23, v23 quad_perm:[3,2,1,0] row_mask:0xf bank_mask:0xf
	s_and_saveexec_b64 s[2:3], s[12:13]
	s_xor_b64 s[18:19], exec, s[2:3]
	s_cbranch_execz .LBB0_260
	s_and_saveexec_b64 s[30:31], s[14:15]
	s_cbranch_execz .LBB0_259
	ds_read_b128 v[60:63], v49 offset:64
	v_mov_b32_e32 v22, v21
	s_waitcnt lgkmcnt(0)
	v_pk_mul_f32 v[22:23], v[62:63], v[22:23]
	v_mul_f32_e32 v20, v60, v20
	v_mul_f32_e32 v52, v61, v51
	v_mov_b32_e32 v21, v22
	v_mov_b32_e32 v53, v23
	v_pk_add_f32 v[20:21], v[20:21], v[52:53]

; #define LAS __attribute__((address_space(3)))
; DI unsigned pk2(float lo, float hi) { f32x2 x = {lo, hi}; return __builtin_bit_cast(unsigned, __builtin_convertvector(x, bf16x2_t)); }
; template <int HP> DI void rope2(f32x2& x, int hl, const LAS f32x2* cs) {
;   const float pa = __shfl_xor(x[0], HP), pb = __shfl_xor(x[1], HP);
;   if (hl < HP) { const f32x2 c0 = cs[2 * hl], c1 = cs[2 * hl + 1]; x[0] = x[0] * c0[0] - pa * c0[1]; x[1] = x[1] * c1[0] - pb * c1[1]; }
;   else if (hl < 2 * HP) { const f32x2 c0 = cs[2 * (hl - HP)], c1 = cs[2 * (hl - HP) + 1]; x[0] = x[0] * c0[0] + pa * c0[1]; x[1] = x[1] * c1[0] + pb * c1[1]; }
; DI void post_unit(const Params& p, int l, int unit, LAS unsigned char* lds) {
;     ...
;       } else if (s < 7) {
;         rope2<4>(x, hl, cs16 + t * 8); *(unsigned*)pp = pk2(x[0], x[1]);
.LBB0_262:
	s_or_b64 exec, exec, s[18:19]
	v_cvt_pk_bf16_f32 v22, v20, v21
	v_add_co_u32_e32 v20, vcc, 0xa002000, v18
	s_nop 1
	v_addc_co_u32_e32 v21, vcc, 0, v19, vcc
	global_store_dword v[20:21], v22, off offset:1792
	s_waitcnt vmcnt(28)
	v_lshlrev_b32_e32 v20, 16, v50
	v_and_b32_e32 v21, 0xffff0000, v50
	s_nop 1
	v_mov_b32_dpp v50, v20 row_half_mirror row_mask:0xf bank_mask:0xf
	s_nop 1
	v_mov_b32_dpp v50, v50 quad_perm:[3,2,1,0] row_mask:0xf bank_mask:0xf
	s_waitcnt lgkmcnt(1)
	s_nop 1
	v_mov_b32_dpp v23, v21 row_half_mirror row_mask:0xf bank_mask:0xf
	s_nop 1
	v_mov_b32_dpp v23, v23 quad_perm:[3,2,1,0] row_mask:0xf bank_mask:0xf
	s_and_saveexec_b64 s[2:3], s[12:13]
	s_xor_b64 s[18:19], exec, s[2:3]
	s_cbranch_execz .LBB0_266
	s_and_saveexec_b64 s[30:31], s[14:15]
	s_cbranch_execz .LBB0_265
	ds_read_b128 v[60:63], v49 offset:64
	v_mov_b32_e32 v22, v21
	s_waitcnt lgkmcnt(0)
	v_pk_mul_f32 v[22:23], v[62:63], v[22:23]
	v_mul_f32_e32 v20, v60, v20
	v_mul_f32_e32 v50, v61, v50
	v_mov_b32_e32 v21, v22
	v_mov_b32_e32 v51, v23
	v_pk_add_f32 v[20:21], v[20:21], v[50:51]

; #define LAS __attribute__((address_space(3)))
; DI unsigned pk2(float lo, float hi) { f32x2 x = {lo, hi}; return __builtin_bit_cast(unsigned, __builtin_convertvector(x, bf16x2_t)); }
; DI float sum32(float v) { v += __shfl_xor(v, 16); return sum16(v); }
; template <int HP> DI void rope2(f32x2& x, int hl, const LAS f32x2* cs) {
;   const float pa = __shfl_xor(x[0], HP), pb = __shfl_xor(x[1], HP);
;   if (hl < HP) { const f32x2 c0 = cs[2 * hl], c1 = cs[2 * hl + 1]; x[0] = x[0] * c0[0] - pa * c0[1]; x[1] = x[1] * c1[0] - pb * c1[1]; }
;   else if (hl < 2 * HP) { const f32x2 c0 = cs[2 * (hl - HP)], c1 = cs[2 * (hl - HP) + 1]; x[0] = x[0] * c0[0] + pa * c0[1]; x[1] = x[1] * c1[0] + pb * c1[1]; }
; DI void post_unit(const Params& p, int l, int unit, LAS unsigned char* lds) {
;     ...
;       } else if (s == 7) {
;         const float rs = rsqrtf(sum32(x[0] * x[0] + x[1] * x[1]) * (1.0f / 64.0f) + EPS);
;         x *= rs; rope2<4>(x, hl, cs16 + t * 8); if (lane < 32) *(unsigned*)((u16*)(p.ws + WS_KIC) + (tok0 + t) * 64 + 2 * lane) = pk2(x[0], x[1]);
.LBB0_268:
	s_or_b64 exec, exec, s[18:19]
	v_cvt_pk_bf16_f32 v22, v20, v21
	v_add_co_u32_e32 v20, vcc, 0xa002000, v18
	s_nop 1
	v_addc_co_u32_e32 v21, vcc, 0, v19, vcc
	global_store_dword v[20:21], v22, off offset:2048
	s_waitcnt vmcnt(28)
	v_lshlrev_b32_e32 v20, 16, v48
	v_and_b32_e32 v21, 0xffff0000, v48
	s_waitcnt lgkmcnt(0)
	v_pk_mul_f32 v[22:23], v[20:21], v[20:21]
	s_nop 0
	v_add_f32_e32 v22, v22, v23
	v_mov_b32_e32 v23, v22
	s_nop 1
	v_permlane16_swap_b32_e32 v22, v23
	v_add_f32_e32 v22, v22, v23
	s_nop 1
	v_add_f32_dpp v22, v22, v22 row_ror:8 row_mask:0xf bank_mask:0xf
	s_nop 1
	v_add_f32_dpp v22, v22, v22 row_ror:4 row_mask:0xf bank_mask:0xf
	s_nop 1
	v_add_f32_dpp v22, v22, v22 quad_perm:[2,3,0,1] row_mask:0xf bank_mask:0xf
	s_nop 1
	v_add_f32_dpp v22, v22, v22 quad_perm:[1,0,3,2] row_mask:0xf bank_mask:0xf
	v_fmamk_f32 v22, v22, 0x3c800000, v170
	v_cmp_gt_f32_e32 vcc, s33, v22
	v_mul_f32_e32 v23, 0x4b800000, v22
	s_nop 0
	v_cndmask_b32_e32 v22, v22, v23, vcc
	v_rsq_f32_e32 v22, v22
	s_nop 0
	v_mul_f32_e32 v23, 0x45800000, v22
	v_cndmask_b32_e32 v22, v22, v23, vcc
	v_pk_mul_f32 v[20:21], v[22:23], v[20:21] op_sel_hi:[0,1]
	s_nop 1
	v_mov_b32_dpp v22, v20 row_half_mirror row_mask:0xf bank_mask:0xf
	v_mov_b32_dpp v23, v21 row_half_mirror row_mask:0xf bank_mask:0xf
	s_nop 0
	v_mov_b32_dpp v22, v22 quad_perm:[3,2,1,0] row_mask:0xf bank_mask:0xf
	v_mov_b32_dpp v23, v23 quad_perm:[3,2,1,0] row_mask:0xf bank_mask:0xf
	s_and_saveexec_b64 s[2:3], s[12:13]
	s_xor_b64 s[18:19], exec, s[2:3]
	s_cbranch_execz .LBB0_316
	s_and_saveexec_b64 s[30:31], s[14:15]
	s_cbranch_execz .LBB0_271
	ds_read_b128 v[48:51], v49 offset:64
	s_waitcnt lgkmcnt(0)
	v_pk_mul_f32 v[52:53], v[20:21], v[48:49]
	v_mul_f32_e32 v20, v49, v22
	v_mov_b32_e32 v22, v21
	v_pk_mul_f32 v[22:23], v[50:51], v[22:23]
	s_nop 0
	v_mov_b32_e32 v53, v22
	v_mov_b32_e32 v21, v23
	v_pk_add_f32 v[20:21], v[52:53], v[20:21]

; #define LAS __attribute__((address_space(3)))
; DI unsigned pk2(float lo, float hi) { f32x2 x = {lo, hi}; return __builtin_bit_cast(unsigned, __builtin_convertvector(x, bf16x2_t)); }
; DI float sum16(float v) { v += __shfl_xor(v, 8); v += __shfl_xor(v, 4); v += __shfl_xor(v, 2); v += __shfl_xor(v, 1); return v; }
; template <int HP> DI void rope2(f32x2& x, int hl, const LAS f32x2* cs) {
;   const float pa = __shfl_xor(x[0], HP), pb = __shfl_xor(x[1], HP);
;   if (hl < HP) { const f32x2 c0 = cs[2 * hl], c1 = cs[2 * hl + 1]; x[0] = x[0] * c0[0] - pa * c0[1]; x[1] = x[1] * c1[0] - pb * c1[1]; }
;   else if (hl < 2 * HP) { const f32x2 c0 = cs[2 * (hl - HP)], c1 = cs[2 * (hl - HP) + 1]; x[0] = x[0] * c0[0] + pa * c0[1]; x[1] = x[1] * c1[0] + pb * c1[1]; }
; DI void post_unit(const Params& p, int l, int unit, LAS unsigned char* lds) {
;     ...
;         const float lg = log1pf(-exp2f(-5.0f - (float)hd));
;         const float f = (s < 10) ? expf(lg * (float)(t + 1)) : expf(lg * (float)(63 - t)) * 0.125f;
;         x *= f; *(unsigned*)pp = pk2(x[0], x[1]);
;       } else {
;         const float* gn = (s < 14) ? qnc : knc;
;         const float rs = rsqrtf(sum16(x[0] * x[0] + x[1] * x[1]) * (1.0f / 32.0f) + EPS);
;         x[0] *= rs * gn[2 * hl16]; x[1] *= rs * gn[2 * hl16 + 1]; rope2<2>(x, hl16, cs8 + t * 4);
;         if (s < 14) x *= LOG2E * 0.17677669529663687f;
;         *(unsigned*)pp = pk2(x[0], x[1]);
.LBB0_290:
	s_or_b64 exec, exec, s[18:19]
	v_mul_f32_e32 v22, v32, v45
	s_waitcnt lgkmcnt(0)
	v_mul_f32_e32 v23, 0x3fb8aa3b, v22
	v_fma_f32 v44, v22, s64, -v23
	v_rndne_f32_e32 v45, v23
	v_fmac_f32_e32 v44, 0x32a5705f, v22
	v_sub_f32_e32 v23, v23, v45
	v_add_f32_e32 v23, v23, v44
	v_exp_f32_e32 v23, v23
	v_cvt_i32_f32_e32 v44, v45
	v_cmp_ngt_f32_e32 vcc, s65, v22
	v_ldexp_f32 v23, v23, v44
	s_nop 0
	v_cndmask_b32_e32 v23, 0, v23, vcc
	v_cmp_nlt_f32_e32 vcc, s89, v22
	s_nop 1
	v_cndmask_b32_e32 v22, v177, v23, vcc
	v_mul_f32_e32 v22, 0x3e000000, v22
	v_pk_mul_f32 v[20:21], v[22:23], v[20:21] op_sel_hi:[0,1]
	v_cvt_pk_bf16_f32 v22, v20, v21
	v_add_co_u32_e32 v20, vcc, s77, v18
	s_nop 1
	v_addc_co_u32_e32 v21, vcc, 0, v19, vcc
	global_store_dword v[20:21], v22, off offset:3712
	s_waitcnt vmcnt(27)
	v_lshlrev_b32_e32 v20, 16, v43
	v_and_b32_e32 v21, 0xffff0000, v43
	v_pk_mul_f32 v[22:23], v[20:21], v[20:21]
	s_nop 0
	v_add_f32_e32 v22, v22, v23
	s_nop 1
	v_add_f32_dpp v22, v22, v22 row_ror:8 row_mask:0xf bank_mask:0xf
	s_nop 1
	v_add_f32_dpp v22, v22, v22 row_ror:4 row_mask:0xf bank_mask:0xf
	s_nop 1
	v_add_f32_dpp v22, v22, v22 quad_perm:[2,3,0,1] row_mask:0xf bank_mask:0xf
	s_nop 1
	v_add_f32_dpp v22, v22, v22 quad_perm:[1,0,3,2] row_mask:0xf bank_mask:0xf
	v_fmamk_f32 v22, v22, 0x3d000000, v170
	v_cmp_gt_f32_e32 vcc, s33, v22
	v_mul_f32_e32 v23, 0x4b800000, v22
	s_nop 0
	v_cndmask_b32_e32 v22, v22, v23, vcc
	v_rsq_f32_e32 v22, v22
	s_nop 0
	v_mul_f32_e32 v23, 0x45800000, v22
	v_cndmask_b32_e32 v22, v22, v23, vcc
	v_pk_mul_f32 v[22:23], v[6:7], v[22:23] op_sel_hi:[1,0]
	s_nop 0
	v_pk_mul_f32 v[22:23], v[22:23], v[20:21]
	s_nop 1
	v_mov_b32_dpp v20, v22 quad_perm:[2,3,0,1] row_mask:0xf bank_mask:0xf
	v_mov_b32_dpp v21, v23 quad_perm:[2,3,0,1] row_mask:0xf bank_mask:0xf
	s_and_saveexec_b64 s[2:3], s[6:7]
	s_xor_b64 s[18:19], exec, s[2:3]
	s_cbranch_execz .LBB0_294
	s_and_saveexec_b64 s[30:31], s[8:9]
	s_cbranch_execz .LBB0_293
	ds_read_b128 v[44:47], v54 offset:32
	s_waitcnt lgkmcnt(0)
	v_pk_mul_f32 v[48:49], v[22:23], v[44:45]
	v_mul_f32_e32 v22, v45, v20
	v_mov_b32_e32 v20, v23
	v_pk_mul_f32 v[20:21], v[20:21], v[46:47]
	s_nop 0
	v_mov_b32_e32 v49, v20
	v_mov_b32_e32 v23, v21
	v_pk_add_f32 v[22:23], v[48:49], v[22:23]

; #define LAS __attribute__((address_space(3)))
; DI unsigned pk2(float lo, float hi) { f32x2 x = {lo, hi}; return __builtin_bit_cast(unsigned, __builtin_convertvector(x, bf16x2_t)); }
; DI float sum16(float v) { v += __shfl_xor(v, 8); v += __shfl_xor(v, 4); v += __shfl_xor(v, 2); v += __shfl_xor(v, 1); return v; }
; template <int HP> DI void rope2(f32x2& x, int hl, const LAS f32x2* cs) {
;   const float pa = __shfl_xor(x[0], HP), pb = __shfl_xor(x[1], HP);
;   if (hl < HP) { const f32x2 c0 = cs[2 * hl], c1 = cs[2 * hl + 1]; x[0] = x[0] * c0[0] - pa * c0[1]; x[1] = x[1] * c1[0] - pb * c1[1]; }
;   else if (hl < 2 * HP) { const f32x2 c0 = cs[2 * (hl - HP)], c1 = cs[2 * (hl - HP) + 1]; x[0] = x[0] * c0[0] + pa * c0[1]; x[1] = x[1] * c1[0] + pb * c1[1]; }
; DI void post_unit(const Params& p, int l, int unit, LAS unsigned char* lds) {
;     ...
;       } else {
;         const float* gn = (s < 14) ? qnc : knc;
;         const float rs = rsqrtf(sum16(x[0] * x[0] + x[1] * x[1]) * (1.0f / 32.0f) + EPS);
;         x[0] *= rs * gn[2 * hl16]; x[1] *= rs * gn[2 * hl16 + 1]; rope2<2>(x, hl16, cs8 + t * 4);
;         if (s < 14) x *= LOG2E * 0.17677669529663687f;
;         *(unsigned*)pp = pk2(x[0], x[1]);
.LBB0_296:
	s_or_b64 exec, exec, s[18:19]
	s_mov_b32 s2, 0x3e8293ee
	s_waitcnt lgkmcnt(0)
	v_pk_mul_f32 v[20:21], v[22:23], s[2:3] op_sel_hi:[1,0]
	s_nop 0
	v_cvt_pk_bf16_f32 v22, v20, v21
	v_add_co_u32_e32 v20, vcc, 0xa003000, v18
	s_nop 1
	v_addc_co_u32_e32 v21, vcc, 0, v19, vcc
	global_store_dword v[20:21], v22, off offset:896
	s_waitcnt vmcnt(27)
	v_lshlrev_b32_e32 v20, 16, v42
	v_and_b32_e32 v21, 0xffff0000, v42
	v_pk_mul_f32 v[22:23], v[20:21], v[20:21]
	s_nop 0
	v_add_f32_e32 v22, v22, v23
	s_nop 1
	v_add_f32_dpp v22, v22, v22 row_ror:8 row_mask:0xf bank_mask:0xf
	s_nop 1
	v_add_f32_dpp v22, v22, v22 row_ror:4 row_mask:0xf bank_mask:0xf
	s_nop 1
	v_add_f32_dpp v22, v22, v22 quad_perm:[2,3,0,1] row_mask:0xf bank_mask:0xf
	s_nop 1
	v_add_f32_dpp v22, v22, v22 quad_perm:[1,0,3,2] row_mask:0xf bank_mask:0xf
	v_fmamk_f32 v22, v22, 0x3d000000, v170
	v_cmp_gt_f32_e32 vcc, s33, v22
	v_mul_f32_e32 v23, 0x4b800000, v22
	s_nop 0
	v_cndmask_b32_e32 v22, v22, v23, vcc
	v_rsq_f32_e32 v22, v22
	s_nop 0
	v_mul_f32_e32 v23, 0x45800000, v22
	v_cndmask_b32_e32 v22, v22, v23, vcc
	v_pk_mul_f32 v[22:23], v[6:7], v[22:23] op_sel_hi:[1,0]
	s_nop 0
	v_pk_mul_f32 v[22:23], v[22:23], v[20:21]
	s_nop 1
	v_mov_b32_dpp v20, v22 quad_perm:[2,3,0,1] row_mask:0xf bank_mask:0xf
	v_mov_b32_dpp v21, v23 quad_perm:[2,3,0,1] row_mask:0xf bank_mask:0xf
	s_and_saveexec_b64 s[2:3], s[6:7]
	s_xor_b64 s[18:19], exec, s[2:3]
	s_cbranch_execz .LBB0_300
	s_and_saveexec_b64 s[30:31], s[8:9]
	s_cbranch_execz .LBB0_299
	ds_read_b128 v[42:45], v54 offset:32
	s_waitcnt lgkmcnt(0)
	v_pk_mul_f32 v[46:47], v[22:23], v[42:43]
	v_mul_f32_e32 v22, v43, v20
	v_mov_b32_e32 v20, v23
	v_pk_mul_f32 v[20:21], v[20:21], v[44:45]
	s_nop 0
	v_mov_b32_e32 v47, v20
	v_mov_b32_e32 v23, v21
	v_pk_add_f32 v[22:23], v[46:47], v[22:23]

; #define LAS __attribute__((address_space(3)))
; DI unsigned pk2(float lo, float hi) { f32x2 x = {lo, hi}; return __builtin_bit_cast(unsigned, __builtin_convertvector(x, bf16x2_t)); }
; DI float sum16(float v) { v += __shfl_xor(v, 8); v += __shfl_xor(v, 4); v += __shfl_xor(v, 2); v += __shfl_xor(v, 1); return v; }
; template <int HP> DI void rope2(f32x2& x, int hl, const LAS f32x2* cs) {
;   const float pa = __shfl_xor(x[0], HP), pb = __shfl_xor(x[1], HP);
;   if (hl < HP) { const f32x2 c0 = cs[2 * hl], c1 = cs[2 * hl + 1]; x[0] = x[0] * c0[0] - pa * c0[1]; x[1] = x[1] * c1[0] - pb * c1[1]; }
;   else if (hl < 2 * HP) { const f32x2 c0 = cs[2 * (hl - HP)], c1 = cs[2 * (hl - HP) + 1]; x[0] = x[0] * c0[0] + pa * c0[1]; x[1] = x[1] * c1[0] + pb * c1[1]; }
; DI void post_unit(const Params& p, int l, int unit, LAS unsigned char* lds) {
;     ...
;       } else {
;         const float* gn = (s < 14) ? qnc : knc;
;         const float rs = rsqrtf(sum16(x[0] * x[0] + x[1] * x[1]) * (1.0f / 32.0f) + EPS);
;         x[0] *= rs * gn[2 * hl16]; x[1] *= rs * gn[2 * hl16 + 1]; rope2<2>(x, hl16, cs8 + t * 4);
;         if (s < 14) x *= LOG2E * 0.17677669529663687f;
;         *(unsigned*)pp = pk2(x[0], x[1]);
.LBB0_302:
	s_or_b64 exec, exec, s[18:19]
	s_mov_b32 s2, 0x3e8293ee
	s_waitcnt lgkmcnt(0)
	v_pk_mul_f32 v[20:21], v[22:23], s[2:3] op_sel_hi:[1,0]
	s_nop 0
	v_cvt_pk_bf16_f32 v22, v20, v21
	v_add_co_u32_e32 v20, vcc, 0xa003000, v18
	s_nop 1
	v_addc_co_u32_e32 v21, vcc, 0, v19, vcc
	global_store_dword v[20:21], v22, off offset:1152
	s_waitcnt vmcnt(27)
	v_lshlrev_b32_e32 v20, 16, v41
	v_and_b32_e32 v21, 0xffff0000, v41
	v_pk_mul_f32 v[22:23], v[20:21], v[20:21]
	s_nop 0
	v_add_f32_e32 v22, v22, v23
	s_nop 1
	v_add_f32_dpp v22, v22, v22 row_ror:8 row_mask:0xf bank_mask:0xf
	s_nop 1
	v_add_f32_dpp v22, v22, v22 row_ror:4 row_mask:0xf bank_mask:0xf
	s_nop 1
	v_add_f32_dpp v22, v22, v22 quad_perm:[2,3,0,1] row_mask:0xf bank_mask:0xf
	s_nop 1
	v_add_f32_dpp v22, v22, v22 quad_perm:[1,0,3,2] row_mask:0xf bank_mask:0xf
	v_fmamk_f32 v22, v22, 0x3d000000, v170
	v_cmp_gt_f32_e32 vcc, s33, v22
	v_mul_f32_e32 v23, 0x4b800000, v22
	s_nop 0
	v_cndmask_b32_e32 v22, v22, v23, vcc
	v_rsq_f32_e32 v22, v22
	s_nop 0
	v_mul_f32_e32 v23, 0x45800000, v22
	v_cndmask_b32_e32 v22, v22, v23, vcc
	v_pk_mul_f32 v[22:23], v[8:9], v[22:23] op_sel_hi:[1,0]
	s_nop 0
	v_pk_mul_f32 v[22:23], v[22:23], v[20:21]
	s_nop 1
	v_mov_b32_dpp v20, v22 quad_perm:[2,3,0,1] row_mask:0xf bank_mask:0xf
	v_mov_b32_dpp v21, v23 quad_perm:[2,3,0,1] row_mask:0xf bank_mask:0xf
	s_and_saveexec_b64 s[2:3], s[6:7]
	s_xor_b64 s[18:19], exec, s[2:3]
	s_cbranch_execz .LBB0_306
	s_and_saveexec_b64 s[30:31], s[8:9]
	s_cbranch_execz .LBB0_305
	ds_read_b128 v[42:45], v54 offset:32
	s_waitcnt lgkmcnt(0)
	v_pk_mul_f32 v[46:47], v[22:23], v[42:43]
	v_mul_f32_e32 v22, v43, v20
	v_mov_b32_e32 v20, v23
	v_pk_mul_f32 v[20:21], v[20:21], v[44:45]
	s_nop 0
	v_mov_b32_e32 v47, v20
	v_mov_b32_e32 v23, v21
	v_pk_add_f32 v[22:23], v[46:47], v[22:23]

; #define LAS __attribute__((address_space(3)))
; DI unsigned pk2(float lo, float hi) { f32x2 x = {lo, hi}; return __builtin_bit_cast(unsigned, __builtin_convertvector(x, bf16x2_t)); }
; DI float sum16(float v) { v += __shfl_xor(v, 8); v += __shfl_xor(v, 4); v += __shfl_xor(v, 2); v += __shfl_xor(v, 1); return v; }
; template <int HP> DI void rope2(f32x2& x, int hl, const LAS f32x2* cs) {
;   const float pa = __shfl_xor(x[0], HP), pb = __shfl_xor(x[1], HP);
;   if (hl < HP) { const f32x2 c0 = cs[2 * hl], c1 = cs[2 * hl + 1]; x[0] = x[0] * c0[0] - pa * c0[1]; x[1] = x[1] * c1[0] - pb * c1[1]; }
;   else if (hl < 2 * HP) { const f32x2 c0 = cs[2 * (hl - HP)], c1 = cs[2 * (hl - HP) + 1]; x[0] = x[0] * c0[0] + pa * c0[1]; x[1] = x[1] * c1[0] + pb * c1[1]; }
; DI void post_unit(const Params& p, int l, int unit, LAS unsigned char* lds) {
;     ...
;       } else {
;         const float* gn = (s < 14) ? qnc : knc;
;         const float rs = rsqrtf(sum16(x[0] * x[0] + x[1] * x[1]) * (1.0f / 32.0f) + EPS);
;         x[0] *= rs * gn[2 * hl16]; x[1] *= rs * gn[2 * hl16 + 1]; rope2<2>(x, hl16, cs8 + t * 4);
;         if (s < 14) x *= LOG2E * 0.17677669529663687f;
;         *(unsigned*)pp = pk2(x[0], x[1]);
.LBB0_308:
	s_or_b64 exec, exec, s[18:19]
	s_waitcnt lgkmcnt(1)
	v_add_co_u32_e32 v20, vcc, 0xa003000, v18
	v_cvt_pk_bf16_f32 v22, v22, v23
	s_waitcnt lgkmcnt(0)
	v_addc_co_u32_e32 v21, vcc, 0, v19, vcc
	global_store_dword v[20:21], v22, off offset:1408
	s_waitcnt vmcnt(27)
	v_lshlrev_b32_e32 v20, 16, v3
	v_and_b32_e32 v21, 0xffff0000, v3
	v_pk_mul_f32 v[22:23], v[20:21], v[20:21]
	s_nop 0
	v_add_f32_e32 v3, v22, v23
	s_nop 1
	v_add_f32_dpp v3, v3, v3 row_ror:8 row_mask:0xf bank_mask:0xf
	s_nop 1
	v_add_f32_dpp v3, v3, v3 row_ror:4 row_mask:0xf bank_mask:0xf
	s_nop 1
	v_add_f32_dpp v3, v3, v3 quad_perm:[2,3,0,1] row_mask:0xf bank_mask:0xf
	s_nop 1
	v_add_f32_dpp v3, v3, v3 quad_perm:[1,0,3,2] row_mask:0xf bank_mask:0xf
	v_fmamk_f32 v3, v3, 0x3d000000, v170
	v_cmp_gt_f32_e32 vcc, s33, v3
	v_mul_f32_e32 v22, 0x4b800000, v3
	s_nop 0
	v_cndmask_b32_e32 v3, v3, v22, vcc
	v_rsq_f32_e32 v3, v3
	s_nop 0
	v_mul_f32_e32 v22, 0x45800000, v3
	v_cndmask_b32_e32 v22, v3, v22, vcc
	v_pk_mul_f32 v[22:23], v[8:9], v[22:23] op_sel_hi:[1,0]
	s_nop 0
	v_pk_mul_f32 v[22:23], v[22:23], v[20:21]
	s_nop 1
	v_mov_b32_dpp v3, v22 quad_perm:[2,3,0,1] row_mask:0xf bank_mask:0xf
	v_mov_b32_dpp v21, v23 quad_perm:[2,3,0,1] row_mask:0xf bank_mask:0xf
	s_and_saveexec_b64 s[2:3], s[6:7]
	s_xor_b64 s[18:19], exec, s[2:3]
	s_cbranch_execz .LBB0_312
	s_and_saveexec_b64 s[30:31], s[8:9]
	s_cbranch_execz .LBB0_311
	ds_read_b128 v[42:45], v54 offset:32
	v_mov_b32_e32 v20, v23
	s_waitcnt lgkmcnt(0)
	v_pk_mul_f32 v[46:47], v[22:23], v[42:43]
	v_pk_mul_f32 v[20:21], v[20:21], v[44:45]
	v_mul_f32_e32 v22, v43, v3
	v_mov_b32_e32 v47, v20
	v_mov_b32_e32 v23, v21
	v_pk_add_f32 v[22:23], v[46:47], v[22:23]
